# v6
# speedup vs baseline: 1.0134x; 1.0134x over previous
; #define LAS __attribute__((address_space(3)))
; #define MFMA32(a, b, c) __builtin_amdgcn_mfma_f32_32x32x16_bf16((a), (b), (c), 0, 0, 0)
; #define SBAR() __builtin_amdgcn_sched_barrier(0)
; DI float max3f(float a, float b, float c) { return __builtin_fmaxf(__builtin_fmaxf(a, b), c); }
; #define AT_GLOADK(kt) do { rk = *(const u32x4*)(kg + (size_t)AT_PT(kt) * 64 * 2048); } while (0)
; DI void attn_step(const LAS unsigned char* Kb, const LAS unsigned char* Vb, f32x16& c0, f32x16& c1, f32x16& n0, f32x16& n1, bf16x8 (&pf)[2][2],
;                   f32x16 (&o)[4], f32x16& negm, float& mrun, float& lrun, const bf16x8 (&qf)[4]) {
;     ...
;     vf[0] = AT_VF(0); vf[1] = AT_VF(1); vf[2] = AT_VF(2);
;     float pm[4];
; #pragma unroll
;     for (int i = 0; i < 4; ++i) {
;         vf[(i + 3) % 4] = AT_VF(i + 3);
;         o[0] = MFMA32(vf[i % 4], pf[(i >> 1) & 1][i & 1], o[0]);
;         const float a = max3f(AT_C(8 * i), AT_C(8 * i + 1), AT_C(8 * i + 2)), b = max3f(AT_C(8 * i + 3), AT_C(8 * i + 4), AT_C(8 * i + 5));
;         pm[i] = max3f(a, b, __builtin_fmaxf(AT_C(8 * i + 6), AT_C(8 * i + 7)));
;         SBAR();
;     }
;     float mx = __builtin_fmaxf(__builtin_fmaxf(pm[0], pm[1]), __builtin_fmaxf(pm[2], pm[3]));
;     { auto rr = __builtin_amdgcn_permlane32_swap(__float_as_uint(mx), __float_as_uint(mx), false, false); mx = __builtin_fmaxf(__uint_as_float(rr[0]), __uint_as_float(rr[1])); }
;     float sc = 1.0f; bool need = false;
;     if (__builtin_expect(__any(mx > AT_THR), 0)) {
; DI void attn_unit(LAS unsigned char* lds, const bf16_t* QK, const bf16_t* VT, bf16_t* O, int mp, int h, int q0, int kt0, int kt1, int coff, int wid0) {
;     ...
; #pragma unroll
;             for (int j = 0; j < 8; ++j) pf[a][b][j] = 0;
;     __syncthreads();
;     f32x16 sa0, sa1, sb0, sb1;
; #pragma unroll
;     for (int r = 0; r < 16; ++r) { sa0[r] = 0.f; sa1[r] = 0.f; }
; #pragma unroll
;     for (int ks = 0; ks < 4; ++ks) {
;         const bf16x8 k0 = *(const LAS bf16x8*)(lds + koff + ks * 32), k1 = *(const LAS bf16x8*)(lds + koff + 32 * KP * 2 + ks * 32);
;         sa0 = MFMA32(k0, qf[ks], sa0); sa1 = MFMA32(k1, qf[ks], sa1);
;     }
;     for (int t = 0; t < nkt; t += 2) {
;         { const int ktk = t + 2 < nkt ? t + 2 : nkt - 1; AT_GLOADK(kt0 + ktk); AT_GLOADV(kt0 + t); }
;         attn_step(lds + AT_K + koff, lds + AT_V + voff, sa0, sa1, sb0, sb1, pf, o, negm, mrun, lrun, qf);
.LBB0_456:
	s_or_b64 exec, exec, s[8:9]
	s_movk_i32 s5, 0x48
	v_mad_u32_u24 v4, v4, s5, v7
	v_lshl_add_u32 v196, v4, 1, 0
	s_waitcnt lgkmcnt(0)
	s_barrier
	ds_read_b128 v[8:11], v196
	ds_read_b128 v[12:15], v196 offset:32
	s_waitcnt lgkmcnt(1)
	v_mfma_f32_32x32x16_bf16 v[96:111], v[8:11], v[128:131], 0
	ds_read_b128 v[8:11], v196 offset:4608
	v_readlane_b32 s8, v253, 56
	v_readlane_b32 s9, v253, 57
	v_add_u32_e32 v2, s4, v2
	s_mov_b32 s5, 0x8400
	v_mov_b64_e32 v[4:5], s[8:9]
	v_mad_i64_i32 v[4:5], s[8:9], v2, s5, v[4:5]
	v_and_b32_e32 v2, 48, v3
	v_add_u32_e32 v1, v1, v2
	v_and_or_b32 v1, v6, 4, v1
	ds_read_b128 v[16:19], v196 offset:4640
	v_lshlrev_b32_e32 v28, 1, v1
	v_mov_b32_e32 v1, v185
	v_lshl_add_u64 v[190:191], v[4:5], 0, v[0:1]
	ds_read_b128 v[0:3], v196 offset:64
	s_waitcnt lgkmcnt(2)
	v_mfma_f32_32x32x16_bf16 v[64:79], v[8:11], v[128:131], 0
	s_mov_b32 s68, 0
	s_mov_b32 s69, s68
	s_mov_b32 s70, s68
	s_mov_b32 s71, s68
	s_mov_b32 s72, s68
	s_mov_b32 s73, s68
	s_mov_b32 s74, s68
	v_mfma_f32_32x32x16_bf16 v[96:111], v[12:15], v[132:135], v[96:111]
	s_mov_b32 s75, s68
	s_mov_b32 s76, s68
	s_mov_b32 s77, s68
	s_mov_b32 s78, s68
	s_mov_b32 s79, s68
	s_mov_b32 s80, s68
	s_mov_b32 s81, s68
	s_waitcnt lgkmcnt(1)
	v_mfma_f32_32x32x16_bf16 v[64:79], v[16:19], v[132:135], v[64:79]
	ds_read_b128 v[16:19], v196 offset:4672
	ds_read_b128 v[20:23], v196 offset:96
	ds_read_b128 v[24:27], v196 offset:4704
	s_mov_b32 s82, s68
	s_mov_b32 s83, s68
	v_mov_b32_e32 v221, 0
	v_add_u32_e32 v197, 0, v28
	v_add_u32_e32 v244, 0x4800, v197
	v_add_u32_e32 v245, 0x6800, v197
	v_add_u32_e32 v246, 0x9000, v197
	v_add_u32_e32 v247, 0xb000, v197
	v_lshl_add_u64 v[192:193], v[190:191], 0, s[84:85]
	s_waitcnt lgkmcnt(3)
	v_mfma_f32_32x32x16_bf16 v[96:111], v[0:3], v[136:139], v[96:111]
	v_mov_b64_e32 v[0:1], s[68:69]
	v_mov_b64_e32 v[14:15], s[82:83]
	v_mov_b64_e32 v[2:3], s[70:71]
	v_mov_b64_e32 v[4:5], s[72:73]
	v_mov_b64_e32 v[6:7], s[74:75]
	v_mov_b64_e32 v[8:9], s[76:77]
	v_mov_b64_e32 v[10:11], s[78:79]
	s_waitcnt lgkmcnt(2)
	v_mfma_f32_32x32x16_bf16 v[64:79], v[16:19], v[136:139], v[64:79]
	v_mov_b64_e32 v[12:13], s[80:81]
	v_mov_b64_e32 v[46:47], v[14:15]
	v_mov_b64_e32 v[62:63], v[14:15]
	v_mov_b32_e32 v156, 0
	v_mov_b32_e32 v157, 0
	v_mov_b32_e32 v158, 0
	v_mov_b32_e32 v159, 0
	s_waitcnt lgkmcnt(1)
	v_mfma_f32_32x32x16_bf16 v[96:111], v[20:23], v[140:143], v[96:111]
	v_mov_b32_e32 v152, 0
	v_mov_b32_e32 v153, 0
	v_mov_b32_e32 v154, 0
	v_mov_b32_e32 v155, 0
	v_mov_b32_e32 v144, 0
	v_mov_b32_e32 v145, 0
	v_mov_b32_e32 v146, 0
	s_waitcnt lgkmcnt(0)
	v_mfma_f32_32x32x16_bf16 v[64:79], v[24:27], v[140:143], v[64:79]
	v_mov_b64_e32 v[30:31], v[14:15]
	v_mov_b32_e32 v147, 0
	v_mov_b32_e32 v148, 0
	v_mov_b32_e32 v149, 0
	v_mov_b32_e32 v150, 0
	v_mov_b32_e32 v151, 0
	v_mov_b64_e32 v[28:29], v[12:13]
	v_mov_b64_e32 v[26:27], v[10:11]
	v_mov_b64_e32 v[24:25], v[8:9]
	v_mov_b64_e32 v[22:23], v[6:7]
	v_mov_b64_e32 v[20:21], v[4:5]
	v_mov_b64_e32 v[18:19], v[2:3]
	v_mov_b64_e32 v[16:17], v[0:1]
	v_mov_b64_e32 v[44:45], v[12:13]
	v_mov_b64_e32 v[42:43], v[10:11]
	v_mov_b64_e32 v[40:41], v[8:9]
	v_mov_b64_e32 v[38:39], v[6:7]
	v_mov_b64_e32 v[36:37], v[4:5]
	v_mov_b64_e32 v[34:35], v[2:3]
	v_mov_b64_e32 v[32:33], v[0:1]
	v_mov_b64_e32 v[60:61], v[12:13]
	v_mov_b64_e32 v[58:59], v[10:11]
	v_mov_b64_e32 v[56:57], v[8:9]
	v_mov_b64_e32 v[54:55], v[6:7]
	v_mov_b64_e32 v[52:53], v[4:5]
	v_mov_b64_e32 v[50:51], v[2:3]
	v_mov_b64_e32 v[48:49], v[0:1]
	v_mov_b32_e32 v198, 0
	v_mov_b32_e32 v112, 0
	v_mov_b32_e32 v113, v221
	v_mov_b32_e32 v114, v221
	v_mov_b32_e32 v115, v221
	v_mov_b32_e32 v116, v221
	v_mov_b32_e32 v117, v221
	v_mov_b32_e32 v118, v221
	v_mov_b32_e32 v119, v221
	v_mov_b32_e32 v120, v221
	v_mov_b32_e32 v121, v221
	v_mov_b32_e32 v122, v221
	v_mov_b32_e32 v123, v221
	v_mov_b32_e32 v124, v221
	v_mov_b32_e32 v125, v221
	v_mov_b32_e32 v126, v221
	v_mov_b32_e32 v127, v221
	v_mov_b32_e32 v194, 1.0
	v_cmp_lt_u32_e32 vcc, 0xff, v199
	s_nop 1
	s_cmp_lg_u64 vcc, 0
	s_cbranch_scc0 .LBB0_457
	ds_read_b128 v[172:175], v196 offset:36864
	ds_read_b128 v[176:179], v196 offset:36896
	ds_read_b128 v[180:183], v196 offset:36928
	ds_read_b128 v[88:91], v196 offset:36960
	s_branch .Lg1_457
.LBB0_457:
	ds_read_b128 v[80:83], v196 offset:36864
	ds_read_b128 v[84:87], v196 offset:36896
	ds_read_b128 v[88:91], v196 offset:36928
	ds_read_b128 v[92:95], v196 offset:36960
	s_add_i32 s5, s68, 2
	s_min_u32 s8, s5, 0x103
	s_cmpk_gt_u32 s68, 0xfd
	s_cselect_b32 s9, s0, 0
	s_add_i32 s9, s9, s8
	s_lshl_b32 s18, s9, 18
	s_cmpk_gt_u32 s68, 0xff
	s_cselect_b32 s8, s0, 0
	s_add_i32 s8, s8, s68
	v_lshl_add_u64 v[240:241], v[188:189], 0, s[18:19]
	s_lshl_b32 s18, s8, 6
	s_lshl_b64 s[8:9], s[18:19], 1
	v_lshl_add_u64 v[242:243], v[190:191], 0, s[8:9]
	global_load_dwordx4 v[168:171], v[240:241], off offset:2048
	global_load_dwordx4 v[164:167], v[242:243], off
	v_lshl_add_u64 v[240:241], v[192:193], 0, s[8:9]
	global_load_dwordx4 v[160:163], v[240:241], off
	s_waitcnt lgkmcnt(3)
	v_mfma_f32_32x32x16_bf16 v[48:63], v[80:83], v[148:151], v[48:63]
	v_max3_f32 v80, v96, v97, v98
	v_max3_f32 v81, v99, v100, v101
	v_max3_f32 v80, v80, v102, v103
	v_max3_f32 v81, v81, v104, v105
	s_waitcnt lgkmcnt(2)
	v_mfma_f32_32x32x16_bf16 v[48:63], v[84:87], v[144:147], v[48:63]
	ds_read_b128 v[172:175], v196 offset:41472
	v_max3_f32 v80, v80, v106, v107
	v_max3_f32 v81, v81, v108, v109
	v_max3_f32 v80, v80, v110, v111
	v_max3_f32 v81, v81, v64, v65
	s_waitcnt lgkmcnt(2)
	v_mfma_f32_32x32x16_bf16 v[48:63], v[88:91], v[152:155], v[48:63]
	ds_read_b128 v[176:179], v196 offset:41504
	v_max3_f32 v80, v80, v66, v67
	v_max3_f32 v81, v81, v68, v69
	v_max3_f32 v80, v80, v70, v71
	v_max3_f32 v81, v81, v72, v73
	s_waitcnt lgkmcnt(2)
	v_mfma_f32_32x32x16_bf16 v[48:63], v[92:95], v[156:159], v[48:63]
	ds_read_b128 v[180:183], v196 offset:41536
	v_max3_f32 v80, v80, v74, v75
	v_max3_f32 v81, v81, v76, v77
	v_max3_f32 v80, v80, v78, v79
	v_max_f32_e32 v80, v80, v81
	v_cmp_lt_f32_e32 vcc, s15, v80
	s_cmp_lg_u64 vcc, 0
	s_cselect_b64 s[8:9], -1, 0
	s_cbranch_vccnz .LBB0_467
; DI unsigned pk2(float lo, float hi) { f32x2 v = {lo, hi}; bf16x2_t b = __builtin_convertvector(v, bf16x2_t); return __builtin_bit_cast(unsigned, b); }
; #define MFMA32(a, b, c) __builtin_amdgcn_mfma_f32_32x32x16_bf16((a), (b), (c), 0, 0, 0)
; #define SBAR() __builtin_amdgcn_sched_barrier(0)
; #define AT_WRITEK(slot) do { *(LAS u32x4*)(lds + (slot) * AT_K + kst) = rk; } while (0)
; DI void attn_step(const LAS unsigned char* Kb, const LAS unsigned char* Vb, f32x16& c0, f32x16& c1, f32x16& n0, f32x16& n1, bf16x8 (&pf)[2][2],
;                   f32x16 (&o)[4], f32x16& negm, float& mrun, float& lrun, const bf16x8 (&qf)[4]) {
;     ...
;     __builtin_amdgcn_s_setprio(1);
; #pragma unroll
;     for (int i = 4; i < 16; ++i) {
;         if (i + 3 < 16) vf[(i + 3) % 4] = AT_VF(i + 3);
;         o[i >> 2] = MFMA32(vf[i % 4], pf[(i >> 1) & 1][i & 1], o[i >> 2]);
;         const int j = i - 4, e0 = j < 8 ? 3 * j : 24 + 2 * (j - 8), ne = j < 8 ? 3 : 2;
; #pragma unroll
;         for (int e = e0; e < e0 + ne; ++e) { if (e < 16) c0[e & 15] = __builtin_amdgcn_exp2f(c0[e & 15]); else c1[e & 15] = __builtin_amdgcn_exp2f(c1[e & 15]); }
;         SBAR();
;     }
;     bf16x8 kf[4];
;     kf[0] = AT_KF(0); kf[1] = AT_KF(1); kf[2] = AT_KF(2);
;     float ls0 = 0.f, ls1 = 0.f; unsigned pw[16];
; #pragma unroll
;     for (int i = 0; i < 8; ++i) {
;         if (i + 3 < 8) kf[(i + 3) % 4] = AT_KF(i + 3);
;         if (i & 1) n1 = MFMA32(kf[i % 4], qf[i >> 1], i < 2 ? negm : n1); else n0 = MFMA32(kf[i % 4], qf[i >> 1], i < 2 ? negm : n0);
;         ls0 += AT_C(4 * i) + AT_C(4 * i + 1); ls1 += AT_C(4 * i + 2) + AT_C(4 * i + 3);
;         pw[2 * i] = pk2(AT_C(4 * i), AT_C(4 * i + 1)); pw[2 * i + 1] = pk2(AT_C(4 * i + 2), AT_C(4 * i + 3));
;         SBAR();
;     }
; #pragma unroll
;     for (int kh = 0; kh < 2; ++kh)
; #pragma unroll
;         for (int s2 = 0; s2 < 2; ++s2) { const u32x4 w = (u32x4){pw[8 * kh + 4 * s2], pw[8 * kh + 4 * s2 + 1], pw[8 * kh + 4 * s2 + 2], pw[8 * kh + 4 * s2 + 3]}; pf[kh][s2] = __builtin_bit_cast(bf16x8, w); }
;     __builtin_amdgcn_s_setprio(0);
;     lrun = lrun * sc + (ls0 + ls1);
; DI void attn_unit(LAS unsigned char* lds, const bf16_t* QK, const bf16_t* VT, bf16_t* O, int mp, int h, int q0, int kt0, int kt1, int coff, int wid0) {
;     ...
;         AT_WRITEK(0); AT_WRITEV(0);
.LBB0_459:
	s_setprio 1
	s_waitcnt lgkmcnt(2)
	v_mfma_f32_32x32x16_bf16 v[32:47], v[172:175], v[148:151], v[32:47]
	ds_read_b128 v[80:83], v196 offset:41568
	v_exp_f32_e32 v92, v96
	v_exp_f32_e32 v93, v97
	v_exp_f32_e32 v94, v98
	s_waitcnt lgkmcnt(2)
	v_mfma_f32_32x32x16_bf16 v[32:47], v[176:179], v[144:147], v[32:47]
	ds_read_b128 v[84:87], v196 offset:46080
	v_exp_f32_e32 v95, v99
	v_exp_f32_e32 v172, v100
	v_exp_f32_e32 v173, v101
	s_waitcnt lgkmcnt(2)
	v_mfma_f32_32x32x16_bf16 v[32:47], v[180:183], v[152:155], v[32:47]
	ds_read_b128 v[96:99], v196 offset:46112
	v_exp_f32_e32 v174, v102
	v_exp_f32_e32 v175, v103
	v_exp_f32_e32 v176, v104
	s_waitcnt lgkmcnt(2)
	v_mfma_f32_32x32x16_bf16 v[32:47], v[80:83], v[156:159], v[32:47]
	ds_read_b128 v[100:103], v196 offset:46144
	v_exp_f32_e32 v177, v105
	v_exp_f32_e32 v178, v106
	v_exp_f32_e32 v179, v107
	s_waitcnt lgkmcnt(2)
	v_mfma_f32_32x32x16_bf16 v[16:31], v[84:87], v[148:151], v[16:31]
	ds_read_b128 v[104:107], v196 offset:46176
	v_exp_f32_e32 v180, v108
	v_exp_f32_e32 v181, v109
	v_exp_f32_e32 v182, v110
	s_waitcnt lgkmcnt(2)
	v_mfma_f32_32x32x16_bf16 v[16:31], v[96:99], v[144:147], v[16:31]
	ds_read_b128 v[80:83], v196 offset:50688
	v_exp_f32_e32 v183, v111
	v_exp_f32_e32 v218, v64
	v_exp_f32_e32 v219, v65
	s_waitcnt lgkmcnt(2)
	v_mfma_f32_32x32x16_bf16 v[16:31], v[100:103], v[152:155], v[16:31]
	ds_read_b128 v[96:99], v196 offset:50720
	v_exp_f32_e32 v222, v66
	v_exp_f32_e32 v223, v67
	v_exp_f32_e32 v224, v68
	s_waitcnt lgkmcnt(2)
	v_mfma_f32_32x32x16_bf16 v[16:31], v[104:107], v[156:159], v[16:31]
	ds_read_b128 v[64:67], v196 offset:50752
	v_exp_f32_e32 v225, v69
	v_exp_f32_e32 v226, v70
	v_exp_f32_e32 v227, v71
	s_waitcnt lgkmcnt(2)
	v_mfma_f32_32x32x16_bf16 v[0:15], v[80:83], v[148:151], v[0:15]
	ds_read_b128 v[68:71], v196 offset:50784
	v_exp_f32_e32 v228, v72
	v_exp_f32_e32 v229, v73
	s_waitcnt lgkmcnt(2)
	v_mfma_f32_32x32x16_bf16 v[0:15], v[96:99], v[144:147], v[0:15]
	v_exp_f32_e32 v230, v74
	v_exp_f32_e32 v231, v75
	s_waitcnt lgkmcnt(1)
	v_mfma_f32_32x32x16_bf16 v[0:15], v[64:67], v[152:155], v[0:15]
	v_exp_f32_e32 v232, v76
	v_exp_f32_e32 v233, v77
	s_waitcnt lgkmcnt(0)
	v_mfma_f32_32x32x16_bf16 v[0:15], v[68:71], v[156:159], v[0:15]
	v_exp_f32_e32 v159, v78
	v_exp_f32_e32 v234, v79
	ds_read_b128 v[64:67], v196 offset:9216
	ds_read_b128 v[80:83], v196 offset:9248
	ds_read_b128 v[84:87], v196 offset:13824
	ds_read_b128 v[88:91], v196 offset:13856
	v_cvt_pk_bf16_f32 v144, v92, v93
	s_waitcnt lgkmcnt(3)
	v_mfma_f32_32x32x16_bf16 v[96:111], v[64:67], v[128:131], v[112:127]
	v_add_f32_e32 v64, v93, v92
	v_add_f32_e32 v65, v95, v94
	v_cvt_pk_bf16_f32 v145, v94, v95
	v_add_f32_e32 v66, v173, v172
	v_add_f32_e32 v148, v66, v64
	v_add_f32_e32 v64, v175, v174
	v_add_f32_e32 v149, v64, v65
	s_waitcnt lgkmcnt(1)
	v_mfma_f32_32x32x16_bf16 v[64:79], v[84:87], v[128:131], v[112:127]
	ds_read_b128 v[92:95], v196 offset:9280
	v_cvt_pk_bf16_f32 v146, v172, v173
	v_cvt_pk_bf16_f32 v147, v174, v175
	v_mfma_f32_32x32x16_bf16 v[96:111], v[80:83], v[132:135], v[96:111]
	ds_read_b128 v[84:87], v196 offset:13888
	v_add_f32_e32 v80, v177, v176
	v_add_f32_e32 v150, v80, v148
	v_add_f32_e32 v80, v179, v178
	v_add_f32_e32 v151, v80, v149
	v_cvt_pk_bf16_f32 v148, v176, v177
	v_cvt_pk_bf16_f32 v149, v178, v179
	s_waitcnt lgkmcnt(2)
	v_mfma_f32_32x32x16_bf16 v[64:79], v[88:91], v[132:135], v[64:79]
	ds_read_b128 v[80:83], v196 offset:9312
	s_waitcnt vmcnt(2)
	ds_write_b128 v195, v[168:171]
	v_add_f32_e32 v88, v181, v180
	v_add_f32_e32 v152, v88, v150
	v_add_f32_e32 v88, v183, v182
	v_add_f32_e32 v153, v88, v151
	v_cvt_pk_bf16_f32 v150, v180, v181
	v_cvt_pk_bf16_f32 v151, v182, v183
	s_waitcnt lgkmcnt(3)
	v_mfma_f32_32x32x16_bf16 v[96:111], v[92:95], v[136:139], v[96:111]
	ds_read_b128 v[88:91], v196 offset:13920
	s_waitcnt vmcnt(1)
	ds_write2_b64 v244, v[164:165], v[166:167] offset1:2
	v_add_f32_e32 v92, v219, v218
	v_add_f32_e32 v93, v223, v222
	v_add_f32_e32 v92, v92, v152
	v_add_f32_e32 v93, v93, v153
	v_cvt_pk_bf16_f32 v152, v218, v219
	v_cvt_pk_bf16_f32 v153, v222, v223
	s_waitcnt lgkmcnt(4)
	v_mfma_f32_32x32x16_bf16 v[64:79], v[84:87], v[136:139], v[64:79]
	s_waitcnt vmcnt(0)
	ds_write2_b64 v245, v[160:161], v[162:163] offset0:128 offset1:130
	v_add_f32_e32 v84, v225, v224
	v_add_f32_e32 v85, v227, v226
	v_cvt_pk_bf16_f32 v154, v224, v225
	v_cvt_pk_bf16_f32 v155, v226, v227
	v_add_f32_e32 v84, v84, v92
	v_add_f32_e32 v85, v85, v93
	s_waitcnt lgkmcnt(4)
	v_mfma_f32_32x32x16_bf16 v[96:111], v[80:83], v[140:143], v[96:111]
	v_add_f32_e32 v80, v229, v228
	v_add_f32_e32 v81, v231, v230
	v_cvt_pk_bf16_f32 v156, v228, v229
	v_cvt_pk_bf16_f32 v157, v230, v231
	v_add_f32_e32 v80, v80, v84
	v_add_f32_e32 v81, v81, v85
	s_waitcnt lgkmcnt(2)
	v_mfma_f32_32x32x16_bf16 v[64:79], v[88:91], v[140:143], v[64:79]
	v_add_f32_e32 v82, v233, v232
	v_add_f32_e32 v80, v82, v80
	v_add_f32_e32 v82, v234, v159
	v_cvt_pk_bf16_f32 v158, v232, v233
	v_cvt_pk_bf16_f32 v159, v159, v234
	v_add_f32_e32 v81, v82, v81
	s_setprio 0
	v_add_f32_e32 v222, v81, v80
	v_fmac_f32_e32 v222, v221, v194
	s_andn2_b64 vcc, exec, s[8:9]
	s_cbranch_vccz .LBB0_468
; DI void attn_step(const LAS unsigned char* Kb, const LAS unsigned char* Vb, f32x16& c0, f32x16& c1, f32x16& n0, f32x16& n1, bf16x8 (&pf)[2][2],
;                   f32x16 (&o)[4], f32x16& negm, float& mrun, float& lrun, const bf16x8 (&qf)[4]) {
;     ...
;     vf[0] = AT_VF(0); vf[1] = AT_VF(1); vf[2] = AT_VF(2);
;     float pm[4];
; #pragma unroll
;     for (int i = 0; i < 4; ++i) {
;         vf[(i + 3) % 4] = AT_VF(i + 3);
;         o[0] = MFMA32(vf[i % 4], pf[(i >> 1) & 1][i & 1], o[0]);
;         const float a = max3f(AT_C(8 * i), AT_C(8 * i + 1), AT_C(8 * i + 2)), b = max3f(AT_C(8 * i + 3), AT_C(8 * i + 4), AT_C(8 * i + 5));
;         pm[i] = max3f(a, b, __builtin_fmaxf(AT_C(8 * i + 6), AT_C(8 * i + 7)));
;         SBAR();
;     }
;     float mx = __builtin_fmaxf(__builtin_fmaxf(pm[0], pm[1]), __builtin_fmaxf(pm[2], pm[3]));
;     { auto rr = __builtin_amdgcn_permlane32_swap(__float_as_uint(mx), __float_as_uint(mx), false, false); mx = __builtin_fmaxf(__uint_as_float(rr[0]), __uint_as_float(rr[1])); }
;     float sc = 1.0f; bool need = false;
;     if (__builtin_expect(__any(mx > AT_THR), 0)) {
;         const float d = mx > AT_THR ? mx : 0.f;
; #pragma unroll
;         for (int r = 0; r < 16; ++r) { c0[r] -= d; c1[r] -= d; }
;         mrun += d; sc = __builtin_amdgcn_exp2f(-d); need = true;
; #pragma unroll
;         for (int r = 0; r < 16; ++r) negm[r] = -mrun;
;     }
;     asm volatile("" : "+v"(negm));
;     __builtin_amdgcn_s_setprio(1);
; #pragma unroll
;     for (int i = 4; i < 16; ++i) {
;         if (i + 3 < 16) vf[(i + 3) % 4] = AT_VF(i + 3);
;         o[i >> 2] = MFMA32(vf[i % 4], pf[(i >> 1) & 1][i & 1], o[i >> 2]);
;         const int j = i - 4, e0 = j < 8 ? 3 * j : 24 + 2 * (j - 8), ne = j < 8 ? 3 : 2;
; #pragma unroll
; DI void attn_unit(LAS unsigned char* lds, const bf16_t* QK, const bf16_t* VT, bf16_t* O, int mp, int h, int q0, int kt0, int kt1, int coff, int wid0) {
;     ...
;         { const int ktk = t + 2 < nkt ? t + 2 : nkt - 1; AT_GLOADK(kt0 + ktk); AT_GLOADV(kt0 + t); }
;         attn_step(lds + AT_K + koff, lds + AT_V + voff, sa0, sa1, sb0, sb1, pf, o, negm, mrun, lrun, qf);
;         AT_WRITEK(0); AT_WRITEV(0);
;         __syncthreads();
;         { const int ktk = t + 3 < nkt ? t + 3 : nkt - 1; AT_GLOADK(kt0 + ktk); AT_GLOADV(kt0 + t + 1); }
;         attn_step(lds + koff, lds + voff, sb0, sb1, sa0, sa1, pf, o, negm, mrun, lrun, qf);
.LBB0_460:
	s_min_u32 s8, s68, 0x100
	s_cmpk_gt_u32 s68, 0xfc
	s_cselect_b32 s9, s0, 0
	s_add_i32 s8, s8, s9
	s_lshl_b32 s8, s8, 18
	s_add_i32 s18, s8, 0xc0000
	s_cmpk_gt_u32 s68, 0xfe
	s_cselect_b32 s8, s0, 0
	s_add_i32 s8, s8, s68
	s_lshl_b32 s8, s8, 6
	v_lshl_add_u64 v[240:241], v[188:189], 0, s[18:19]
	s_add_i32 s18, s8, 64
	s_lshl_b64 s[8:9], s[18:19], 1
	s_waitcnt lgkmcnt(0)
	s_barrier
	ds_read_b128 v[80:83], v196 offset:18432
	ds_read_b128 v[84:87], v196 offset:18464
	ds_read_b128 v[88:91], v196 offset:18496
	ds_read_b128 v[92:95], v196 offset:18528
	v_lshl_add_u64 v[242:243], v[190:191], 0, s[8:9]
	global_load_dwordx4 v[168:171], v[240:241], off offset:2048
	global_load_dwordx4 v[164:167], v[242:243], off
	v_lshl_add_u64 v[240:241], v[192:193], 0, s[8:9]
	global_load_dwordx4 v[160:163], v[240:241], off
	s_waitcnt lgkmcnt(3)
	v_mfma_f32_32x32x16_bf16 v[48:63], v[80:83], v[144:147], v[48:63]
	v_max3_f32 v80, v96, v97, v98
	v_max3_f32 v81, v99, v100, v101
	v_max3_f32 v80, v80, v102, v103
	v_max3_f32 v81, v81, v104, v105
	s_waitcnt lgkmcnt(2)
	v_mfma_f32_32x32x16_bf16 v[48:63], v[84:87], v[148:151], v[48:63]
	ds_read_b128 v[172:175], v196 offset:23040
	v_max3_f32 v80, v80, v106, v107
	v_max3_f32 v81, v81, v108, v109
	v_max3_f32 v80, v80, v110, v111
	v_max3_f32 v81, v81, v64, v65
	s_waitcnt lgkmcnt(2)
	v_mfma_f32_32x32x16_bf16 v[48:63], v[88:91], v[152:155], v[48:63]
	ds_read_b128 v[176:179], v196 offset:23072
	v_max3_f32 v80, v80, v66, v67
	v_max3_f32 v81, v81, v68, v69
	v_max3_f32 v80, v80, v70, v71
	v_max3_f32 v81, v81, v72, v73
	s_waitcnt lgkmcnt(2)
	v_mfma_f32_32x32x16_bf16 v[48:63], v[92:95], v[156:159], v[48:63]
	ds_read_b128 v[180:183], v196 offset:23104
	v_max3_f32 v80, v80, v74, v75
	v_max3_f32 v81, v81, v76, v77
	v_max3_f32 v80, v80, v78, v79
	v_max_f32_e32 v80, v80, v81
	v_cmp_lt_f32_e32 vcc, s15, v80
	s_cmp_lg_u64 vcc, 0
	s_cselect_b64 s[8:9], -1, 0
	s_cbranch_vccnz .LBB0_469
.LBB0_464:
	s_setprio 1
	s_waitcnt lgkmcnt(2)
	v_mfma_f32_32x32x16_bf16 v[32:47], v[172:175], v[144:147], v[32:47]
	ds_read_b128 v[80:83], v196 offset:23136
	v_exp_f32_e32 v172, v96
	v_exp_f32_e32 v173, v97
	v_exp_f32_e32 v174, v98
	s_waitcnt lgkmcnt(2)
	v_mfma_f32_32x32x16_bf16 v[32:47], v[176:179], v[148:151], v[32:47]
	ds_read_b128 v[84:87], v196 offset:27648
	v_exp_f32_e32 v175, v99
	v_exp_f32_e32 v176, v100
	v_exp_f32_e32 v177, v101
	s_waitcnt lgkmcnt(2)
	v_mfma_f32_32x32x16_bf16 v[32:47], v[180:183], v[152:155], v[32:47]
	ds_read_b128 v[88:91], v196 offset:27680
	v_exp_f32_e32 v178, v102
	v_exp_f32_e32 v179, v103
	v_exp_f32_e32 v180, v104
	s_waitcnt lgkmcnt(2)
	v_mfma_f32_32x32x16_bf16 v[32:47], v[80:83], v[156:159], v[32:47]
	ds_read_b128 v[92:95], v196 offset:27712
	v_exp_f32_e32 v181, v105
	v_exp_f32_e32 v182, v106
	v_exp_f32_e32 v183, v107
	s_waitcnt lgkmcnt(2)
	v_mfma_f32_32x32x16_bf16 v[16:31], v[84:87], v[144:147], v[16:31]
	ds_read_b128 v[80:83], v196 offset:27744
	v_exp_f32_e32 v239, v108
	v_exp_f32_e32 v218, v109
	v_exp_f32_e32 v219, v110
	s_waitcnt lgkmcnt(2)
	v_mfma_f32_32x32x16_bf16 v[16:31], v[88:91], v[148:151], v[16:31]
	ds_read_b128 v[84:87], v196 offset:32256
	v_exp_f32_e32 v221, v111
	v_exp_f32_e32 v224, v64
	v_exp_f32_e32 v225, v65
	s_waitcnt lgkmcnt(2)
	v_mfma_f32_32x32x16_bf16 v[16:31], v[92:95], v[152:155], v[16:31]
	ds_read_b128 v[88:91], v196 offset:32288
	v_exp_f32_e32 v226, v66
	v_exp_f32_e32 v227, v67
	v_exp_f32_e32 v228, v68
	s_waitcnt lgkmcnt(2)
	v_mfma_f32_32x32x16_bf16 v[16:31], v[80:83], v[156:159], v[16:31]
	ds_read_b128 v[64:67], v196 offset:32320
	v_exp_f32_e32 v229, v69
	v_exp_f32_e32 v230, v70
	v_exp_f32_e32 v231, v71
	s_waitcnt lgkmcnt(2)
	v_mfma_f32_32x32x16_bf16 v[0:15], v[84:87], v[144:147], v[0:15]
	ds_read_b128 v[68:71], v196 offset:32352
	v_exp_f32_e32 v232, v72
	v_exp_f32_e32 v233, v73
	s_waitcnt lgkmcnt(2)
	v_mfma_f32_32x32x16_bf16 v[0:15], v[88:91], v[148:151], v[0:15]
	v_exp_f32_e32 v234, v74
	v_exp_f32_e32 v235, v75
	s_waitcnt lgkmcnt(1)
	v_mfma_f32_32x32x16_bf16 v[0:15], v[64:67], v[152:155], v[0:15]
	v_exp_f32_e32 v236, v76
	v_exp_f32_e32 v237, v77
	s_waitcnt lgkmcnt(0)
	v_mfma_f32_32x32x16_bf16 v[0:15], v[68:71], v[156:159], v[0:15]
	v_exp_f32_e32 v159, v78
	v_exp_f32_e32 v238, v79
	ds_read_b128 v[64:67], v196
	ds_read_b128 v[80:83], v196 offset:32
	ds_read_b128 v[84:87], v196 offset:4608
	ds_read_b128 v[88:91], v196 offset:4640
	v_cvt_pk_bf16_f32 v148, v172, v173
	s_waitcnt lgkmcnt(3)
	v_mfma_f32_32x32x16_bf16 v[96:111], v[64:67], v[128:131], v[112:127]
	v_add_f32_e32 v64, v173, v172
	v_add_f32_e32 v65, v175, v174
	v_cvt_pk_bf16_f32 v149, v174, v175
	v_add_f32_e32 v66, v177, v176
	v_add_f32_e32 v144, v66, v64
	v_add_f32_e32 v64, v179, v178
	v_add_f32_e32 v145, v64, v65
	s_waitcnt lgkmcnt(1)
	v_mfma_f32_32x32x16_bf16 v[64:79], v[84:87], v[128:131], v[112:127]
	ds_read_b128 v[92:95], v196 offset:64
	v_cvt_pk_bf16_f32 v150, v176, v177
	v_cvt_pk_bf16_f32 v151, v178, v179
	v_mfma_f32_32x32x16_bf16 v[96:111], v[80:83], v[132:135], v[96:111]
	ds_read_b128 v[84:87], v196 offset:4672
	v_add_f32_e32 v80, v181, v180
	v_add_f32_e32 v146, v80, v144
	v_add_f32_e32 v80, v183, v182
	v_add_f32_e32 v147, v80, v145
	v_cvt_pk_bf16_f32 v144, v180, v181
	v_cvt_pk_bf16_f32 v145, v182, v183
	s_waitcnt lgkmcnt(2)
	v_mfma_f32_32x32x16_bf16 v[64:79], v[88:91], v[132:135], v[64:79]
	ds_read_b128 v[80:83], v196 offset:96
	s_waitcnt vmcnt(2)
	ds_write_b128 v195, v[168:171] offset:9216
	v_add_f32_e32 v88, v218, v239
	v_add_f32_e32 v152, v88, v146
	v_add_f32_e32 v88, v221, v219
	v_add_f32_e32 v153, v88, v147
	v_cvt_pk_bf16_f32 v146, v239, v218
	v_cvt_pk_bf16_f32 v147, v219, v221
	s_waitcnt lgkmcnt(3)
; DI unsigned pk2(float lo, float hi) { f32x2 v = {lo, hi}; bf16x2_t b = __builtin_convertvector(v, bf16x2_t); return __builtin_bit_cast(unsigned, b); }
; #define MFMA32(a, b, c) __builtin_amdgcn_mfma_f32_32x32x16_bf16((a), (b), (c), 0, 0, 0)
; #define SBAR() __builtin_amdgcn_sched_barrier(0)
; #define AT_WRITEK(slot) do { *(LAS u32x4*)(lds + (slot) * AT_K + kst) = rk; } while (0)
; #define AT_WRITEV(slot) do { LAS unsigned char* b_ = lds + (slot) * AT_V + vst; *(LAS u32x2*)(b_) = (u32x2){rv0.x, rv0.y}; *(LAS u32x2*)(b_ + 16) = (u32x2){rv0.z, rv0.w}; \
;         *(LAS u32x2*)(b_ + 64 * VP * 2) = (u32x2){rv1.x, rv1.y}; *(LAS u32x2*)(b_ + 64 * VP * 2 + 16) = (u32x2){rv1.z, rv1.w}; } while (0)
; DI void attn_step(const LAS unsigned char* Kb, const LAS unsigned char* Vb, f32x16& c0, f32x16& c1, f32x16& n0, f32x16& n1, bf16x8 (&pf)[2][2],
;                   f32x16 (&o)[4], f32x16& negm, float& mrun, float& lrun, const bf16x8 (&qf)[4]) {
;     ...
;     kf[0] = AT_KF(0); kf[1] = AT_KF(1); kf[2] = AT_KF(2);
;     float ls0 = 0.f, ls1 = 0.f; unsigned pw[16];
; #pragma unroll
;     for (int i = 0; i < 8; ++i) {
;         if (i + 3 < 8) kf[(i + 3) % 4] = AT_KF(i + 3);
;         if (i & 1) n1 = MFMA32(kf[i % 4], qf[i >> 1], i < 2 ? negm : n1); else n0 = MFMA32(kf[i % 4], qf[i >> 1], i < 2 ? negm : n0);
;         ls0 += AT_C(4 * i) + AT_C(4 * i + 1); ls1 += AT_C(4 * i + 2) + AT_C(4 * i + 3);
;         pw[2 * i] = pk2(AT_C(4 * i), AT_C(4 * i + 1)); pw[2 * i + 1] = pk2(AT_C(4 * i + 2), AT_C(4 * i + 3));
;         SBAR();
;     }
; #pragma unroll
;     for (int kh = 0; kh < 2; ++kh)
; #pragma unroll
;         for (int s2 = 0; s2 < 2; ++s2) { const u32x4 w = (u32x4){pw[8 * kh + 4 * s2], pw[8 * kh + 4 * s2 + 1], pw[8 * kh + 4 * s2 + 2], pw[8 * kh + 4 * s2 + 3]}; pf[kh][s2] = __builtin_bit_cast(bf16x8, w); }
;     __builtin_amdgcn_s_setprio(0);
;     lrun = lrun * sc + (ls0 + ls1);
;     asm volatile("" : "+v"(pf[0][0]), "+v"(pf[0][1]), "+v"(pf[1][0]), "+v"(pf[1][1]), "+v"(lrun), "+v"(n0), "+v"(n1));
; DI void attn_unit(LAS unsigned char* lds, const bf16_t* QK, const bf16_t* VT, bf16_t* O, int mp, int h, int q0, int kt0, int kt1, int coff, int wid0) {
;     ...
;         attn_step(lds + koff, lds + voff, sb0, sb1, sa0, sa1, pf, o, negm, mrun, lrun, qf);
;         AT_WRITEK(1); AT_WRITEV(1);
;         __syncthreads();
	v_mfma_f32_32x32x16_bf16 v[96:111], v[92:95], v[136:139], v[96:111]
	ds_read_b128 v[88:91], v196 offset:4704
	s_waitcnt vmcnt(1)
	ds_write2_b64 v246, v[164:165], v[166:167] offset1:2
	v_add_f32_e32 v92, v225, v224
	v_add_f32_e32 v93, v227, v226
	v_add_f32_e32 v92, v92, v152
	v_add_f32_e32 v93, v93, v153
	v_cvt_pk_bf16_f32 v152, v224, v225
	v_cvt_pk_bf16_f32 v153, v226, v227
	s_waitcnt lgkmcnt(4)
	v_mfma_f32_32x32x16_bf16 v[64:79], v[84:87], v[136:139], v[64:79]
	s_waitcnt vmcnt(0)
	ds_write2_b64 v247, v[160:161], v[162:163] offset0:128 offset1:130
	v_add_f32_e32 v84, v229, v228
	v_add_f32_e32 v85, v231, v230
	v_cvt_pk_bf16_f32 v154, v228, v229
	v_cvt_pk_bf16_f32 v155, v230, v231
	v_add_f32_e32 v84, v84, v92
	v_add_f32_e32 v85, v85, v93
	s_waitcnt lgkmcnt(4)
	v_mfma_f32_32x32x16_bf16 v[96:111], v[80:83], v[140:143], v[96:111]
	v_add_f32_e32 v80, v233, v232
	v_add_f32_e32 v81, v235, v234
	v_cvt_pk_bf16_f32 v156, v232, v233
	v_cvt_pk_bf16_f32 v157, v234, v235
	v_add_f32_e32 v80, v80, v84
	v_add_f32_e32 v81, v81, v85
	s_waitcnt lgkmcnt(2)
	v_mfma_f32_32x32x16_bf16 v[64:79], v[88:91], v[140:143], v[64:79]
	v_add_f32_e32 v82, v237, v236
	v_add_f32_e32 v80, v82, v80
	v_add_f32_e32 v82, v238, v159
	v_cvt_pk_bf16_f32 v158, v236, v237
	v_cvt_pk_bf16_f32 v159, v159, v238
	v_add_f32_e32 v81, v82, v81
	s_setprio 0
	v_add_f32_e32 v221, v81, v80
	v_fmac_f32_e32 v221, v222, v194
	s_andn2_b64 vcc, exec, s[8:9]
	s_cbranch_vccz .LBB0_470
.LBB0_465:
	s_cmpk_lt_u32 s68, 0x102
	s_waitcnt lgkmcnt(0)
	s_barrier
	s_cbranch_scc0 .LBB0_438
	s_mov_b32 s68, s5
	s_branch .LBB0_457
.LBB0_467:
	v_mov_b32_e32 v81, v80
	s_nop 1
	v_permlane32_swap_b32_e32 v80, v81
	v_max_f32_e32 v80, v80, v81
	v_cmp_lt_f32_e32 vcc, s15, v80
	s_nop 1
	v_cndmask_b32_e32 v82, 0, v80, vcc
	v_exp_f32_e64 v194, -v82
	v_add_f32_e32 v198, v198, v82
	v_xor_b32_e32 v112, 0x80000000, v198
	v_pk_add_f32 v[96:97], v[96:97], v[82:83] op_sel_hi:[1,0] neg_lo:[0,1] neg_hi:[0,1]
	v_pk_add_f32 v[64:65], v[64:65], v[82:83] op_sel_hi:[1,0] neg_lo:[0,1] neg_hi:[0,1]
	v_pk_add_f32 v[98:99], v[98:99], v[82:83] op_sel_hi:[1,0] neg_lo:[0,1] neg_hi:[0,1]
	v_pk_add_f32 v[66:67], v[66:67], v[82:83] op_sel_hi:[1,0] neg_lo:[0,1] neg_hi:[0,1]
	v_pk_add_f32 v[100:101], v[100:101], v[82:83] op_sel_hi:[1,0] neg_lo:[0,1] neg_hi:[0,1]
	v_pk_add_f32 v[68:69], v[68:69], v[82:83] op_sel_hi:[1,0] neg_lo:[0,1] neg_hi:[0,1]
	v_pk_add_f32 v[102:103], v[102:103], v[82:83] op_sel_hi:[1,0] neg_lo:[0,1] neg_hi:[0,1]
	v_pk_add_f32 v[70:71], v[70:71], v[82:83] op_sel_hi:[1,0] neg_lo:[0,1] neg_hi:[0,1]
	v_pk_add_f32 v[104:105], v[104:105], v[82:83] op_sel_hi:[1,0] neg_lo:[0,1] neg_hi:[0,1]
	v_pk_add_f32 v[72:73], v[72:73], v[82:83] op_sel_hi:[1,0] neg_lo:[0,1] neg_hi:[0,1]
	v_pk_add_f32 v[106:107], v[106:107], v[82:83] op_sel_hi:[1,0] neg_lo:[0,1] neg_hi:[0,1]
	v_pk_add_f32 v[74:75], v[74:75], v[82:83] op_sel_hi:[1,0] neg_lo:[0,1] neg_hi:[0,1]
	v_pk_add_f32 v[108:109], v[108:109], v[82:83] op_sel_hi:[1,0] neg_lo:[0,1] neg_hi:[0,1]
	v_pk_add_f32 v[76:77], v[76:77], v[82:83] op_sel_hi:[1,0] neg_lo:[0,1] neg_hi:[0,1]
	v_pk_add_f32 v[110:111], v[110:111], v[82:83] op_sel_hi:[1,0] neg_lo:[0,1] neg_hi:[0,1]
	v_pk_add_f32 v[78:79], v[78:79], v[82:83] op_sel_hi:[1,0] neg_lo:[0,1] neg_hi:[0,1]
	v_mov_b32_e32 v113, v112
	v_mov_b32_e32 v114, v112
	v_mov_b32_e32 v115, v112
	v_mov_b32_e32 v116, v112
	v_mov_b32_e32 v117, v112
	v_mov_b32_e32 v118, v112
	v_mov_b32_e32 v119, v112
	v_mov_b32_e32 v120, v112
	v_mov_b32_e32 v121, v112
	v_mov_b32_e32 v122, v112
	v_mov_b32_e32 v123, v112
	v_mov_b32_e32 v124, v112
	v_mov_b32_e32 v125, v112
	v_mov_b32_e32 v126, v112
	v_mov_b32_e32 v127, v112
	s_branch .LBB0_459
; DI void attn_step(const LAS unsigned char* Kb, const LAS unsigned char* Vb, f32x16& c0, f32x16& c1, f32x16& n0, f32x16& n1, bf16x8 (&pf)[2][2],
;                   f32x16 (&o)[4], f32x16& negm, float& mrun, float& lrun, const bf16x8 (&qf)[4]) {
;     ...
;     if (__builtin_expect(__any(mx > AT_THR), 0)) {
;         const float d = mx > AT_THR ? mx : 0.f;
; #pragma unroll
;         for (int r = 0; r < 16; ++r) { c0[r] -= d; c1[r] -= d; }
;         mrun += d; sc = __builtin_amdgcn_exp2f(-d); need = true;
; #pragma unroll
;         for (int r = 0; r < 16; ++r) negm[r] = -mrun;
;     }
;     ...
;     if (__builtin_expect(need, 0)) {
; #pragma unroll
;         for (int d = 0; d < 4; ++d)
; #pragma unroll
;             for (int r = 0; r < 16; ++r) o[d][r] *= sc;
;     }
.LBB0_468:
	v_pk_mul_f32 v[62:63], v[62:63], v[194:195] op_sel_hi:[1,0]
	v_pk_mul_f32 v[60:61], v[60:61], v[194:195] op_sel_hi:[1,0]
	v_pk_mul_f32 v[58:59], v[58:59], v[194:195] op_sel_hi:[1,0]
	v_pk_mul_f32 v[56:57], v[56:57], v[194:195] op_sel_hi:[1,0]
	v_pk_mul_f32 v[54:55], v[54:55], v[194:195] op_sel_hi:[1,0]
	v_pk_mul_f32 v[52:53], v[52:53], v[194:195] op_sel_hi:[1,0]
	v_pk_mul_f32 v[50:51], v[50:51], v[194:195] op_sel_hi:[1,0]
	v_pk_mul_f32 v[48:49], v[48:49], v[194:195] op_sel_hi:[1,0]
	v_pk_mul_f32 v[46:47], v[194:195], v[46:47] op_sel_hi:[0,1]
	v_pk_mul_f32 v[44:45], v[194:195], v[44:45] op_sel_hi:[0,1]
	v_pk_mul_f32 v[42:43], v[194:195], v[42:43] op_sel_hi:[0,1]
	v_pk_mul_f32 v[40:41], v[194:195], v[40:41] op_sel_hi:[0,1]
	v_pk_mul_f32 v[38:39], v[194:195], v[38:39] op_sel_hi:[0,1]
	v_pk_mul_f32 v[36:37], v[194:195], v[36:37] op_sel_hi:[0,1]
	v_pk_mul_f32 v[34:35], v[194:195], v[34:35] op_sel_hi:[0,1]
	v_pk_mul_f32 v[32:33], v[194:195], v[32:33] op_sel_hi:[0,1]
	v_pk_mul_f32 v[30:31], v[194:195], v[30:31] op_sel_hi:[0,1]
	v_pk_mul_f32 v[28:29], v[194:195], v[28:29] op_sel_hi:[0,1]
	v_pk_mul_f32 v[26:27], v[194:195], v[26:27] op_sel_hi:[0,1]
	v_pk_mul_f32 v[24:25], v[194:195], v[24:25] op_sel_hi:[0,1]
	v_pk_mul_f32 v[22:23], v[194:195], v[22:23] op_sel_hi:[0,1]
	v_pk_mul_f32 v[20:21], v[194:195], v[20:21] op_sel_hi:[0,1]
	v_pk_mul_f32 v[18:19], v[194:195], v[18:19] op_sel_hi:[0,1]
	v_pk_mul_f32 v[16:17], v[194:195], v[16:17] op_sel_hi:[0,1]
	v_pk_mul_f32 v[14:15], v[194:195], v[14:15] op_sel_hi:[0,1]
	v_pk_mul_f32 v[12:13], v[194:195], v[12:13] op_sel_hi:[0,1]
	v_pk_mul_f32 v[10:11], v[194:195], v[10:11] op_sel_hi:[0,1]
	v_pk_mul_f32 v[8:9], v[194:195], v[8:9] op_sel_hi:[0,1]
	v_pk_mul_f32 v[6:7], v[194:195], v[6:7] op_sel_hi:[0,1]
	v_pk_mul_f32 v[4:5], v[194:195], v[4:5] op_sel_hi:[0,1]
	v_pk_mul_f32 v[2:3], v[194:195], v[2:3] op_sel_hi:[0,1]
	v_pk_mul_f32 v[0:1], v[194:195], v[0:1] op_sel_hi:[0,1]
	v_mov_b32_e32 v194, 1.0
	s_branch .LBB0_460
.LBB0_469:
	v_mov_b32_e32 v81, v80
	s_nop 1
	v_permlane32_swap_b32_e32 v80, v81
	v_max_f32_e32 v80, v80, v81
	v_cmp_lt_f32_e32 vcc, s15, v80
	s_nop 1
	v_cndmask_b32_e32 v80, 0, v80, vcc
	v_add_f32_e32 v198, v198, v80
	v_pk_add_f32 v[96:97], v[96:97], v[80:81] op_sel_hi:[1,0] neg_lo:[0,1] neg_hi:[0,1]
	v_pk_add_f32 v[64:65], v[64:65], v[80:81] op_sel_hi:[1,0] neg_lo:[0,1] neg_hi:[0,1]
	v_pk_add_f32 v[98:99], v[98:99], v[80:81] op_sel_hi:[1,0] neg_lo:[0,1] neg_hi:[0,1]
	v_pk_add_f32 v[66:67], v[66:67], v[80:81] op_sel_hi:[1,0] neg_lo:[0,1] neg_hi:[0,1]
	v_pk_add_f32 v[100:101], v[100:101], v[80:81] op_sel_hi:[1,0] neg_lo:[0,1] neg_hi:[0,1]
	v_pk_add_f32 v[68:69], v[68:69], v[80:81] op_sel_hi:[1,0] neg_lo:[0,1] neg_hi:[0,1]
	v_pk_add_f32 v[102:103], v[102:103], v[80:81] op_sel_hi:[1,0] neg_lo:[0,1] neg_hi:[0,1]
	v_pk_add_f32 v[70:71], v[70:71], v[80:81] op_sel_hi:[1,0] neg_lo:[0,1] neg_hi:[0,1]
	v_pk_add_f32 v[104:105], v[104:105], v[80:81] op_sel_hi:[1,0] neg_lo:[0,1] neg_hi:[0,1]
	v_pk_add_f32 v[72:73], v[72:73], v[80:81] op_sel_hi:[1,0] neg_lo:[0,1] neg_hi:[0,1]
	v_pk_add_f32 v[106:107], v[106:107], v[80:81] op_sel_hi:[1,0] neg_lo:[0,1] neg_hi:[0,1]
	v_pk_add_f32 v[74:75], v[74:75], v[80:81] op_sel_hi:[1,0] neg_lo:[0,1] neg_hi:[0,1]
	v_pk_add_f32 v[108:109], v[108:109], v[80:81] op_sel_hi:[1,0] neg_lo:[0,1] neg_hi:[0,1]
	v_pk_add_f32 v[76:77], v[76:77], v[80:81] op_sel_hi:[1,0] neg_lo:[0,1] neg_hi:[0,1]
	v_pk_add_f32 v[110:111], v[110:111], v[80:81] op_sel_hi:[1,0] neg_lo:[0,1] neg_hi:[0,1]
	v_pk_add_f32 v[78:79], v[78:79], v[80:81] op_sel_hi:[1,0] neg_lo:[0,1] neg_hi:[0,1]
	v_exp_f32_e64 v194, -v80
	v_xor_b32_e32 v112, 0x80000000, v198
	v_mov_b32_e32 v113, v112
	v_mov_b32_e32 v114, v112
	v_mov_b32_e32 v115, v112
	v_mov_b32_e32 v116, v112
	v_mov_b32_e32 v117, v112
	v_mov_b32_e32 v118, v112
	v_mov_b32_e32 v119, v112
	v_mov_b32_e32 v120, v112
	v_mov_b32_e32 v121, v112
	v_mov_b32_e32 v122, v112
	v_mov_b32_e32 v123, v112
	v_mov_b32_e32 v124, v112
	v_mov_b32_e32 v125, v112
	v_mov_b32_e32 v126, v112
	v_mov_b32_e32 v127, v112
	s_branch .LBB0_464

; DI void attn_step(const LAS unsigned char* Kb, const LAS unsigned char* Vb, f32x16& c0, f32x16& c1, f32x16& n0, f32x16& n1, bf16x8 (&pf)[2][2],
;                   f32x16 (&o)[4], f32x16& negm, float& mrun, float& lrun, const bf16x8 (&qf)[4]) {
;     ...
;     vf[0] = AT_VF(0); vf[1] = AT_VF(1); vf[2] = AT_VF(2);
;     float pm[4];
; #pragma unroll
;     for (int i = 0; i < 4; ++i) {
;         vf[(i + 3) % 4] = AT_VF(i + 3);
;         o[0] = MFMA32(vf[i % 4], pf[(i >> 1) & 1][i & 1], o[0]);
;         const float a = max3f(AT_C(8 * i), AT_C(8 * i + 1), AT_C(8 * i + 2)), b = max3f(AT_C(8 * i + 3), AT_C(8 * i + 4), AT_C(8 * i + 5));
;         pm[i] = max3f(a, b, __builtin_fmaxf(AT_C(8 * i + 6), AT_C(8 * i + 7)));
;         SBAR();
;     }
;     float mx = __builtin_fmaxf(__builtin_fmaxf(pm[0], pm[1]), __builtin_fmaxf(pm[2], pm[3]));
;     { auto rr = __builtin_amdgcn_permlane32_swap(__float_as_uint(mx), __float_as_uint(mx), false, false); mx = __builtin_fmaxf(__uint_as_float(rr[0]), __uint_as_float(rr[1])); }
;     float sc = 1.0f; bool need = false;
;     if (__builtin_expect(__any(mx > AT_THR), 0)) {
;         const float d = mx > AT_THR ? mx : 0.f;
; #pragma unroll
;         for (int r = 0; r < 16; ++r) { c0[r] -= d; c1[r] -= d; }
;         mrun += d; sc = __builtin_amdgcn_exp2f(-d); need = true;
; #pragma unroll
;         for (int r = 0; r < 16; ++r) negm[r] = -mrun;
;     }
;     asm volatile("" : "+v"(negm));
;     __builtin_amdgcn_s_setprio(1);
; #pragma unroll
;     for (int i = 4; i < 16; ++i) {
;         if (i + 3 < 16) vf[(i + 3) % 4] = AT_VF(i + 3);
;         o[i >> 2] = MFMA32(vf[i % 4], pf[(i >> 1) & 1][i & 1], o[i >> 2]);
;         const int j = i - 4, e0 = j < 8 ? 3 * j : 24 + 2 * (j - 8), ne = j < 8 ? 3 : 2;
; #pragma unroll
;         for (int e = e0; e < e0 + ne; ++e) { if (e < 16) c0[e & 15] = __builtin_amdgcn_exp2f(c0[e & 15]); else c1[e & 15] = __builtin_amdgcn_exp2f(c1[e & 15]); }
;         SBAR();
;     }
; DI void attn_unit(LAS unsigned char* lds, const bf16_t* QK, const bf16_t* VT, bf16_t* O, int mp, int h, int q0, int kt0, int kt1, int coff, int wid0) {
;     ...
;         { const int ktk = t + 2 < nkt ? t + 2 : nkt - 1; AT_GLOADK(kt0 + ktk); AT_GLOADV(kt0 + t); }
;         attn_step(lds + AT_K + koff, lds + AT_V + voff, sa0, sa1, sb0, sb1, pf, o, negm, mrun, lrun, qf);
;         AT_WRITEK(0); AT_WRITEV(0);
;         __syncthreads();
.Lg1_457:
	s_add_i32 s5, s68, 2
	s_min_u32 s8, s5, 0x103
	s_cmpk_gt_u32 s68, 0xfd
	s_cselect_b32 s9, s0, 0
	s_add_i32 s9, s9, s8
	s_lshl_b32 s18, s9, 18
	s_cmpk_gt_u32 s68, 0xff
	s_cselect_b32 s8, s0, 0
	s_add_i32 s8, s8, s68
	v_lshl_add_u64 v[240:241], v[188:189], 0, s[18:19]
	s_lshl_b32 s18, s8, 6
	s_lshl_b64 s[8:9], s[18:19], 1
	v_lshl_add_u64 v[242:243], v[190:191], 0, s[8:9]
	global_load_dwordx4 v[168:171], v[240:241], off offset:2048
	global_load_dwordx4 v[164:167], v[242:243], off
	v_lshl_add_u64 v[240:241], v[192:193], 0, s[8:9]
	global_load_dwordx4 v[160:163], v[240:241], off
	s_waitcnt lgkmcnt(3)
	v_mfma_f32_32x32x16_bf16 v[48:63], v[172:175], v[148:151], v[48:63]
	v_max3_f32 v80, v96, v97, v98
	v_max3_f32 v81, v99, v100, v101
	v_max3_f32 v80, v80, v102, v103
	v_max3_f32 v81, v81, v104, v105
	s_waitcnt lgkmcnt(2)
	v_mfma_f32_32x32x16_bf16 v[48:63], v[176:179], v[144:147], v[48:63]
	ds_read_b128 v[172:175], v196 offset:41472
	v_max3_f32 v80, v80, v106, v107
	v_max3_f32 v81, v81, v108, v109
	v_max3_f32 v80, v80, v110, v111
	v_max3_f32 v81, v81, v64, v65
	s_waitcnt lgkmcnt(2)
	v_mfma_f32_32x32x16_bf16 v[48:63], v[180:183], v[152:155], v[48:63]
	ds_read_b128 v[176:179], v196 offset:41504
	v_max3_f32 v80, v80, v66, v67
	v_max3_f32 v81, v81, v68, v69
	v_max3_f32 v80, v80, v70, v71
	v_max3_f32 v81, v81, v72, v73
	s_waitcnt lgkmcnt(2)
	v_mfma_f32_32x32x16_bf16 v[48:63], v[88:91], v[156:159], v[48:63]
	ds_read_b128 v[180:183], v196 offset:41536
	v_max3_f32 v80, v80, v74, v75
	v_max3_f32 v81, v81, v76, v77
	v_max3_f32 v80, v80, v78, v79
	v_max_f32_e32 v80, v80, v81
	v_cmp_lt_f32_e32 vcc, s15, v80
	s_cmp_lg_u64 vcc, 0
	s_cselect_b64 s[8:9], -1, 0
	s_cbranch_vccnz .Lg1_467
.Lg1_459:
	s_setprio 1
	s_waitcnt lgkmcnt(2)
	v_mfma_f32_32x32x16_bf16 v[32:47], v[172:175], v[148:151], v[32:47]
	ds_read_b128 v[80:83], v196 offset:41568
	v_exp_f32_e32 v92, v96
	v_exp_f32_e32 v93, v97
	v_exp_f32_e32 v94, v98
	s_waitcnt lgkmcnt(2)
	v_mfma_f32_32x32x16_bf16 v[32:47], v[176:179], v[144:147], v[32:47]
	ds_read_b128 v[84:87], v196 offset:46080
	v_exp_f32_e32 v95, v99
	v_exp_f32_e32 v172, v100
	v_exp_f32_e32 v173, v101
	s_waitcnt lgkmcnt(2)
	v_mfma_f32_32x32x16_bf16 v[32:47], v[180:183], v[152:155], v[32:47]
	ds_read_b128 v[96:99], v196 offset:46112
	v_exp_f32_e32 v174, v102
	v_exp_f32_e32 v175, v103
	v_exp_f32_e32 v176, v104
	s_waitcnt lgkmcnt(2)
	v_mfma_f32_32x32x16_bf16 v[32:47], v[80:83], v[156:159], v[32:47]
	ds_read_b128 v[100:103], v196 offset:46144
	v_exp_f32_e32 v177, v105
	v_exp_f32_e32 v178, v106
	v_exp_f32_e32 v179, v107
	s_waitcnt lgkmcnt(2)
	v_mfma_f32_32x32x16_bf16 v[16:31], v[84:87], v[148:151], v[16:31]
	ds_read_b128 v[104:107], v196 offset:46176
	v_exp_f32_e32 v180, v108
	v_exp_f32_e32 v181, v109
	v_exp_f32_e32 v182, v110
	s_waitcnt lgkmcnt(2)
	v_mfma_f32_32x32x16_bf16 v[16:31], v[96:99], v[144:147], v[16:31]
	ds_read_b128 v[80:83], v196 offset:50688
	v_exp_f32_e32 v183, v111
	v_exp_f32_e32 v218, v64
	v_exp_f32_e32 v219, v65
	s_waitcnt lgkmcnt(2)
	v_mfma_f32_32x32x16_bf16 v[16:31], v[100:103], v[152:155], v[16:31]
	ds_read_b128 v[96:99], v196 offset:50720
	v_exp_f32_e32 v222, v66
	v_exp_f32_e32 v223, v67
	v_exp_f32_e32 v224, v68
	s_waitcnt lgkmcnt(2)
	v_mfma_f32_32x32x16_bf16 v[16:31], v[104:107], v[156:159], v[16:31]
	ds_read_b128 v[64:67], v196 offset:50752
	v_exp_f32_e32 v225, v69
	v_exp_f32_e32 v226, v70
	v_exp_f32_e32 v227, v71
	s_waitcnt lgkmcnt(2)
	v_mfma_f32_32x32x16_bf16 v[0:15], v[80:83], v[148:151], v[0:15]
	ds_read_b128 v[68:71], v196 offset:50784
	v_exp_f32_e32 v228, v72
	v_exp_f32_e32 v229, v73
	s_waitcnt lgkmcnt(2)
	v_mfma_f32_32x32x16_bf16 v[0:15], v[96:99], v[144:147], v[0:15]
	v_exp_f32_e32 v230, v74
	v_exp_f32_e32 v231, v75
	s_waitcnt lgkmcnt(1)
	v_mfma_f32_32x32x16_bf16 v[0:15], v[64:67], v[152:155], v[0:15]
	v_exp_f32_e32 v232, v76
	v_exp_f32_e32 v233, v77
	s_waitcnt lgkmcnt(0)
	v_mfma_f32_32x32x16_bf16 v[0:15], v[68:71], v[156:159], v[0:15]
	v_exp_f32_e32 v159, v78
	v_exp_f32_e32 v234, v79
	ds_read_b128 v[64:67], v196 offset:9216
	ds_read_b128 v[80:83], v196 offset:9248
	ds_read_b128 v[84:87], v196 offset:13824
	ds_read_b128 v[88:91], v196 offset:13856
	v_cvt_pk_bf16_f32 v144, v92, v93
	s_waitcnt lgkmcnt(3)
	v_mfma_f32_32x32x16_bf16 v[96:111], v[64:67], v[128:131], v[112:127]
	v_add_f32_e32 v64, v93, v92
	v_add_f32_e32 v65, v95, v94
	v_cvt_pk_bf16_f32 v145, v94, v95
	v_add_f32_e32 v66, v173, v172
	v_add_f32_e32 v148, v66, v64
	v_add_f32_e32 v64, v175, v174
	v_add_f32_e32 v149, v64, v65
	s_waitcnt lgkmcnt(1)
	v_mfma_f32_32x32x16_bf16 v[64:79], v[84:87], v[128:131], v[112:127]
	ds_read_b128 v[92:95], v196 offset:9280
	s_waitcnt vmcnt(2)
	ds_write_b128 v195, v[168:171]
	v_cvt_pk_bf16_f32 v146, v172, v173
	v_cvt_pk_bf16_f32 v147, v174, v175
	v_mfma_f32_32x32x16_bf16 v[96:111], v[80:83], v[132:135], v[96:111]
	ds_read_b128 v[84:87], v196 offset:13888
	v_add_f32_e32 v80, v177, v176
	v_add_f32_e32 v150, v80, v148
	v_add_f32_e32 v80, v179, v178
	v_add_f32_e32 v151, v80, v149
	v_cvt_pk_bf16_f32 v148, v176, v177
	v_cvt_pk_bf16_f32 v149, v178, v179
	ds_read_b128 v[80:83], v196 offset:9312
	ds_read_b128 v[248:251], v196 offset:13920
	s_waitcnt vmcnt(1)
	ds_write2_b64 v244, v[164:165], v[166:167] offset1:2
	s_waitcnt lgkmcnt(6)
	v_mfma_f32_32x32x16_bf16 v[64:79], v[88:91], v[132:135], v[64:79]
	s_waitcnt vmcnt(0)
	ds_write2_b64 v245, v[160:161], v[162:163] offset0:128 offset1:130
	v_add_f32_e32 v88, v181, v180
	v_add_f32_e32 v152, v88, v150
	v_add_f32_e32 v88, v183, v182
	v_add_f32_e32 v153, v88, v151
	v_cvt_pk_bf16_f32 v150, v180, v181
	v_cvt_pk_bf16_f32 v151, v182, v183
	s_waitcnt lgkmcnt(0)
	s_barrier
	ds_read_b128 v[172:175], v196 offset:18432
	ds_read_b128 v[176:179], v196 offset:18464
	ds_read_b128 v[180:183], v196 offset:18496
	ds_read_b128 v[88:91], v196 offset:18528
	v_mfma_f32_32x32x16_bf16 v[96:111], v[92:95], v[136:139], v[96:111]
	v_add_f32_e32 v92, v219, v218
	v_add_f32_e32 v93, v223, v222
	v_add_f32_e32 v92, v92, v152
	v_add_f32_e32 v93, v93, v153
	v_cvt_pk_bf16_f32 v152, v218, v219
	v_cvt_pk_bf16_f32 v153, v222, v223
	v_mfma_f32_32x32x16_bf16 v[64:79], v[84:87], v[136:139], v[64:79]
	v_add_f32_e32 v84, v225, v224
	v_add_f32_e32 v85, v227, v226
	v_cvt_pk_bf16_f32 v154, v224, v225
	v_cvt_pk_bf16_f32 v155, v226, v227
	v_add_f32_e32 v84, v84, v92
	v_add_f32_e32 v85, v85, v93
	v_mfma_f32_32x32x16_bf16 v[96:111], v[80:83], v[140:143], v[96:111]
	v_add_f32_e32 v80, v229, v228
	v_add_f32_e32 v81, v231, v230
	v_cvt_pk_bf16_f32 v156, v228, v229
	v_cvt_pk_bf16_f32 v157, v230, v231
	v_add_f32_e32 v80, v80, v84
	v_add_f32_e32 v81, v81, v85
	v_mfma_f32_32x32x16_bf16 v[64:79], v[248:251], v[140:143], v[64:79]
	v_add_f32_e32 v82, v233, v232
	v_add_f32_e32 v80, v82, v80
	v_add_f32_e32 v82, v234, v159
	v_cvt_pk_bf16_f32 v158, v232, v233
	v_cvt_pk_bf16_f32 v159, v159, v234
	v_add_f32_e32 v81, v82, v81
	s_setprio 0
	v_add_f32_e32 v222, v81, v80
	v_fmac_f32_e32 v222, v221, v194
	s_andn2_b64 vcc, exec, s[8:9]
	s_cbranch_vccz .Lg1_468
; #define MFMA32(a, b, c) __builtin_amdgcn_mfma_f32_32x32x16_bf16((a), (b), (c), 0, 0, 0)
; #define SBAR() __builtin_amdgcn_sched_barrier(0)
; DI float max3f(float a, float b, float c) { return __builtin_fmaxf(__builtin_fmaxf(a, b), c); }
; #define AT_GLOADK(kt) do { rk = *(const u32x4*)(kg + (size_t)AT_PT(kt) * 64 * 2048); } while (0)
; #define AT_GLOADV(kt) do { rv0 = *(const u32x4*)(vg + AT_PT(kt) * 64); rv1 = *(const u32x4*)(vg + (size_t)64 * ROWS + AT_PT(kt) * 64); } while (0)
; DI void attn_step(const LAS unsigned char* Kb, const LAS unsigned char* Vb, f32x16& c0, f32x16& c1, f32x16& n0, f32x16& n1, bf16x8 (&pf)[2][2],
;                   f32x16 (&o)[4], f32x16& negm, float& mrun, float& lrun, const bf16x8 (&qf)[4]) {
;     ...
;     vf[0] = AT_VF(0); vf[1] = AT_VF(1); vf[2] = AT_VF(2);
;     float pm[4];
; #pragma unroll
;     for (int i = 0; i < 4; ++i) {
;         vf[(i + 3) % 4] = AT_VF(i + 3);
;         o[0] = MFMA32(vf[i % 4], pf[(i >> 1) & 1][i & 1], o[0]);
;         const float a = max3f(AT_C(8 * i), AT_C(8 * i + 1), AT_C(8 * i + 2)), b = max3f(AT_C(8 * i + 3), AT_C(8 * i + 4), AT_C(8 * i + 5));
;         pm[i] = max3f(a, b, __builtin_fmaxf(AT_C(8 * i + 6), AT_C(8 * i + 7)));
;         SBAR();
;     }
;     float mx = __builtin_fmaxf(__builtin_fmaxf(pm[0], pm[1]), __builtin_fmaxf(pm[2], pm[3]));
;     { auto rr = __builtin_amdgcn_permlane32_swap(__float_as_uint(mx), __float_as_uint(mx), false, false); mx = __builtin_fmaxf(__uint_as_float(rr[0]), __uint_as_float(rr[1])); }
;     float sc = 1.0f; bool need = false;
;     if (__builtin_expect(__any(mx > AT_THR), 0)) {
; DI void attn_unit(LAS unsigned char* lds, const bf16_t* QK, const bf16_t* VT, bf16_t* O, int mp, int h, int q0, int kt0, int kt1, int coff, int wid0) {
;     ...
;         { const int ktk = t + 3 < nkt ? t + 3 : nkt - 1; AT_GLOADK(kt0 + ktk); AT_GLOADV(kt0 + t + 1); }
;         attn_step(lds + koff, lds + voff, sb0, sb1, sa0, sa1, pf, o, negm, mrun, lrun, qf);
.Lg1_460:
	s_min_u32 s8, s68, 0x100
	s_cmpk_gt_u32 s68, 0xfc
	s_cselect_b32 s9, s0, 0
	s_add_i32 s8, s8, s9
	s_lshl_b32 s8, s8, 18
	s_add_i32 s18, s8, 0xc0000
	s_cmpk_gt_u32 s68, 0xfe
	s_cselect_b32 s8, s0, 0
	s_add_i32 s8, s8, s68
	s_lshl_b32 s8, s8, 6
	v_lshl_add_u64 v[240:241], v[188:189], 0, s[18:19]
	s_add_i32 s18, s8, 64
	s_lshl_b64 s[8:9], s[18:19], 1
	v_lshl_add_u64 v[242:243], v[190:191], 0, s[8:9]
	global_load_dwordx4 v[168:171], v[240:241], off offset:2048
	global_load_dwordx4 v[164:167], v[242:243], off
	v_lshl_add_u64 v[240:241], v[192:193], 0, s[8:9]
	global_load_dwordx4 v[160:163], v[240:241], off
	s_waitcnt lgkmcnt(3)
	v_mfma_f32_32x32x16_bf16 v[48:63], v[172:175], v[144:147], v[48:63]
	v_max3_f32 v80, v96, v97, v98
	v_max3_f32 v81, v99, v100, v101
	v_max3_f32 v80, v80, v102, v103
	v_max3_f32 v81, v81, v104, v105
	s_waitcnt lgkmcnt(2)
	v_mfma_f32_32x32x16_bf16 v[48:63], v[176:179], v[148:151], v[48:63]
	ds_read_b128 v[172:175], v196 offset:23040
	v_max3_f32 v80, v80, v106, v107
	v_max3_f32 v81, v81, v108, v109
	v_max3_f32 v80, v80, v110, v111
	v_max3_f32 v81, v81, v64, v65
	s_waitcnt lgkmcnt(2)
	v_mfma_f32_32x32x16_bf16 v[48:63], v[180:183], v[152:155], v[48:63]
	ds_read_b128 v[176:179], v196 offset:23072
	v_max3_f32 v80, v80, v66, v67
	v_max3_f32 v81, v81, v68, v69
	v_max3_f32 v80, v80, v70, v71
	v_max3_f32 v81, v81, v72, v73
	s_waitcnt lgkmcnt(2)
	v_mfma_f32_32x32x16_bf16 v[48:63], v[88:91], v[156:159], v[48:63]
	ds_read_b128 v[180:183], v196 offset:23104
	v_max3_f32 v80, v80, v74, v75
	v_max3_f32 v81, v81, v76, v77
	v_max3_f32 v80, v80, v78, v79
	v_max_f32_e32 v80, v80, v81
	v_cmp_lt_f32_e32 vcc, s15, v80
	s_cmp_lg_u64 vcc, 0
	s_cselect_b64 s[8:9], -1, 0
	s_cbranch_vccnz .Lg1_469
; DI unsigned pk2(float lo, float hi) { f32x2 v = {lo, hi}; bf16x2_t b = __builtin_convertvector(v, bf16x2_t); return __builtin_bit_cast(unsigned, b); }
; #define SBAR() __builtin_amdgcn_sched_barrier(0)
; DI void attn_step(const LAS unsigned char* Kb, const LAS unsigned char* Vb, f32x16& c0, f32x16& c1, f32x16& n0, f32x16& n1, bf16x8 (&pf)[2][2],
;                   f32x16 (&o)[4], f32x16& negm, float& mrun, float& lrun, const bf16x8 (&qf)[4]) {
;     ...
;         for (int r = 0; r < 16; ++r) negm[r] = -mrun;
;     }
;     asm volatile("" : "+v"(negm));
;     __builtin_amdgcn_s_setprio(1);
; #pragma unroll
;     for (int i = 4; i < 16; ++i) {
;         if (i + 3 < 16) vf[(i + 3) % 4] = AT_VF(i + 3);
;         o[i >> 2] = MFMA32(vf[i % 4], pf[(i >> 1) & 1][i & 1], o[i >> 2]);
;         const int j = i - 4, e0 = j < 8 ? 3 * j : 24 + 2 * (j - 8), ne = j < 8 ? 3 : 2;
; #pragma unroll
;         for (int e = e0; e < e0 + ne; ++e) { if (e < 16) c0[e & 15] = __builtin_amdgcn_exp2f(c0[e & 15]); else c1[e & 15] = __builtin_amdgcn_exp2f(c1[e & 15]); }
;         SBAR();
;     }
;     bf16x8 kf[4];
;     kf[0] = AT_KF(0); kf[1] = AT_KF(1); kf[2] = AT_KF(2);
;     float ls0 = 0.f, ls1 = 0.f; unsigned pw[16];
; #pragma unroll
;     for (int i = 0; i < 8; ++i) {
;         if (i + 3 < 8) kf[(i + 3) % 4] = AT_KF(i + 3);
;         if (i & 1) n1 = MFMA32(kf[i % 4], qf[i >> 1], i < 2 ? negm : n1); else n0 = MFMA32(kf[i % 4], qf[i >> 1], i < 2 ? negm : n0);
;         ls0 += AT_C(4 * i) + AT_C(4 * i + 1); ls1 += AT_C(4 * i + 2) + AT_C(4 * i + 3);
;         pw[2 * i] = pk2(AT_C(4 * i), AT_C(4 * i + 1)); pw[2 * i + 1] = pk2(AT_C(4 * i + 2), AT_C(4 * i + 3));
;         SBAR();
;     }
; #pragma unroll
;     for (int kh = 0; kh < 2; ++kh)
; #pragma unroll
;         for (int s2 = 0; s2 < 2; ++s2) { const u32x4 w = (u32x4){pw[8 * kh + 4 * s2], pw[8 * kh + 4 * s2 + 1], pw[8 * kh + 4 * s2 + 2], pw[8 * kh + 4 * s2 + 3]}; pf[kh][s2] = __builtin_bit_cast(bf16x8, w); }
;     __builtin_amdgcn_s_setprio(0);
;     lrun = lrun * sc + (ls0 + ls1);
;     asm volatile("" : "+v"(pf[0][0]), "+v"(pf[0][1]), "+v"(pf[1][0]), "+v"(pf[1][1]), "+v"(lrun), "+v"(n0), "+v"(n1));
; DI void attn_unit(LAS unsigned char* lds, const bf16_t* QK, const bf16_t* VT, bf16_t* O, int mp, int h, int q0, int kt0, int kt1, int coff, int wid0) {
;     ...
;         AT_WRITEK(1); AT_WRITEV(1);
;         __syncthreads();
.Lg1_464:
	s_setprio 1
	s_waitcnt lgkmcnt(2)
	v_mfma_f32_32x32x16_bf16 v[32:47], v[172:175], v[144:147], v[32:47]
	ds_read_b128 v[80:83], v196 offset:23136
	v_exp_f32_e32 v172, v96
	v_exp_f32_e32 v173, v97
	v_exp_f32_e32 v174, v98
	s_waitcnt lgkmcnt(2)
	v_mfma_f32_32x32x16_bf16 v[32:47], v[176:179], v[148:151], v[32:47]
	ds_read_b128 v[84:87], v196 offset:27648
	v_exp_f32_e32 v175, v99
	v_exp_f32_e32 v176, v100
	v_exp_f32_e32 v177, v101
	s_waitcnt lgkmcnt(2)
	v_mfma_f32_32x32x16_bf16 v[32:47], v[180:183], v[152:155], v[32:47]
	ds_read_b128 v[88:91], v196 offset:27680
	v_exp_f32_e32 v178, v102
	v_exp_f32_e32 v179, v103
	v_exp_f32_e32 v180, v104
	s_waitcnt lgkmcnt(2)
	v_mfma_f32_32x32x16_bf16 v[32:47], v[80:83], v[156:159], v[32:47]
	ds_read_b128 v[92:95], v196 offset:27712
	v_exp_f32_e32 v181, v105
	v_exp_f32_e32 v182, v106
	v_exp_f32_e32 v183, v107
	s_waitcnt lgkmcnt(2)
	v_mfma_f32_32x32x16_bf16 v[16:31], v[84:87], v[144:147], v[16:31]
	ds_read_b128 v[80:83], v196 offset:27744
	v_exp_f32_e32 v239, v108
	v_exp_f32_e32 v218, v109
	v_exp_f32_e32 v219, v110
	s_waitcnt lgkmcnt(2)
	v_mfma_f32_32x32x16_bf16 v[16:31], v[88:91], v[148:151], v[16:31]
	ds_read_b128 v[84:87], v196 offset:32256
	v_exp_f32_e32 v221, v111
	v_exp_f32_e32 v224, v64
	v_exp_f32_e32 v225, v65
	s_waitcnt lgkmcnt(2)
	v_mfma_f32_32x32x16_bf16 v[16:31], v[92:95], v[152:155], v[16:31]
	ds_read_b128 v[88:91], v196 offset:32288
	v_exp_f32_e32 v226, v66
	v_exp_f32_e32 v227, v67
	v_exp_f32_e32 v228, v68
	s_waitcnt lgkmcnt(2)
	v_mfma_f32_32x32x16_bf16 v[16:31], v[80:83], v[156:159], v[16:31]
	ds_read_b128 v[64:67], v196 offset:32320
	v_exp_f32_e32 v229, v69
	v_exp_f32_e32 v230, v70
	v_exp_f32_e32 v231, v71
	s_waitcnt lgkmcnt(2)
	v_mfma_f32_32x32x16_bf16 v[0:15], v[84:87], v[144:147], v[0:15]
	ds_read_b128 v[68:71], v196 offset:32352
	v_exp_f32_e32 v232, v72
	v_exp_f32_e32 v233, v73
	s_waitcnt lgkmcnt(2)
	v_mfma_f32_32x32x16_bf16 v[0:15], v[88:91], v[148:151], v[0:15]
	v_exp_f32_e32 v234, v74
	v_exp_f32_e32 v235, v75
	s_waitcnt lgkmcnt(1)
	v_mfma_f32_32x32x16_bf16 v[0:15], v[64:67], v[152:155], v[0:15]
	v_exp_f32_e32 v236, v76
	v_exp_f32_e32 v237, v77
	s_waitcnt lgkmcnt(0)
	v_mfma_f32_32x32x16_bf16 v[0:15], v[68:71], v[156:159], v[0:15]
	v_exp_f32_e32 v159, v78
	v_exp_f32_e32 v238, v79
	ds_read_b128 v[64:67], v196
	ds_read_b128 v[80:83], v196 offset:32
	ds_read_b128 v[84:87], v196 offset:4608
	ds_read_b128 v[88:91], v196 offset:4640
	v_cvt_pk_bf16_f32 v148, v172, v173
	s_waitcnt lgkmcnt(3)
	v_mfma_f32_32x32x16_bf16 v[96:111], v[64:67], v[128:131], v[112:127]
	v_add_f32_e32 v64, v173, v172
	v_add_f32_e32 v65, v175, v174
	v_cvt_pk_bf16_f32 v149, v174, v175
	v_add_f32_e32 v66, v177, v176
	v_add_f32_e32 v144, v66, v64
	v_add_f32_e32 v64, v179, v178
	v_add_f32_e32 v145, v64, v65
	s_waitcnt lgkmcnt(1)
	v_mfma_f32_32x32x16_bf16 v[64:79], v[84:87], v[128:131], v[112:127]
	ds_read_b128 v[92:95], v196 offset:64
	s_waitcnt vmcnt(2)
	ds_write_b128 v195, v[168:171] offset:9216
	v_cvt_pk_bf16_f32 v150, v176, v177
	v_cvt_pk_bf16_f32 v151, v178, v179
	v_mfma_f32_32x32x16_bf16 v[96:111], v[80:83], v[132:135], v[96:111]
	ds_read_b128 v[84:87], v196 offset:4672
	v_add_f32_e32 v80, v181, v180
	v_add_f32_e32 v146, v80, v144
	v_add_f32_e32 v80, v183, v182
	v_add_f32_e32 v147, v80, v145
	v_cvt_pk_bf16_f32 v144, v180, v181
	v_cvt_pk_bf16_f32 v145, v182, v183
	ds_read_b128 v[80:83], v196 offset:96
	ds_read_b128 v[248:251], v196 offset:4704
	s_waitcnt vmcnt(1)
	ds_write2_b64 v246, v[164:165], v[166:167] offset1:2
	s_waitcnt lgkmcnt(6)
	v_mfma_f32_32x32x16_bf16 v[64:79], v[88:91], v[132:135], v[64:79]
	s_waitcnt vmcnt(0)
	ds_write2_b64 v247, v[160:161], v[162:163] offset0:128 offset1:130
	v_add_f32_e32 v88, v218, v239
	v_add_f32_e32 v152, v88, v146
	v_add_f32_e32 v88, v221, v219
	v_add_f32_e32 v153, v88, v147
	v_cvt_pk_bf16_f32 v146, v239, v218
	v_cvt_pk_bf16_f32 v147, v219, v221
	s_waitcnt lgkmcnt(0)
	s_barrier
	ds_read_b128 v[172:175], v196 offset:36864
	ds_read_b128 v[176:179], v196 offset:36896
	ds_read_b128 v[180:183], v196 offset:36928
	ds_read_b128 v[88:91], v196 offset:36960
	v_mfma_f32_32x32x16_bf16 v[96:111], v[92:95], v[136:139], v[96:111]
	v_add_f32_e32 v92, v225, v224
	v_add_f32_e32 v93, v227, v226
	v_add_f32_e32 v92, v92, v152
	v_add_f32_e32 v93, v93, v153
	v_cvt_pk_bf16_f32 v152, v224, v225
	v_cvt_pk_bf16_f32 v153, v226, v227
	v_mfma_f32_32x32x16_bf16 v[64:79], v[84:87], v[136:139], v[64:79]
	v_add_f32_e32 v84, v229, v228
	v_add_f32_e32 v85, v231, v230
	v_cvt_pk_bf16_f32 v154, v228, v229
	v_cvt_pk_bf16_f32 v155, v230, v231
	v_add_f32_e32 v84, v84, v92
	v_add_f32_e32 v85, v85, v93
	v_mfma_f32_32x32x16_bf16 v[96:111], v[80:83], v[140:143], v[96:111]
	v_add_f32_e32 v80, v233, v232
	v_add_f32_e32 v81, v235, v234
	v_cvt_pk_bf16_f32 v156, v232, v233
	v_cvt_pk_bf16_f32 v157, v234, v235
	v_add_f32_e32 v80, v80, v84
	v_add_f32_e32 v81, v81, v85
	v_mfma_f32_32x32x16_bf16 v[64:79], v[248:251], v[140:143], v[64:79]
	v_add_f32_e32 v82, v237, v236
	v_add_f32_e32 v80, v82, v80
	v_add_f32_e32 v82, v238, v159
	v_cvt_pk_bf16_f32 v158, v236, v237
	v_cvt_pk_bf16_f32 v159, v159, v238
	v_add_f32_e32 v81, v82, v81
	s_setprio 0
	v_add_f32_e32 v221, v81, v80
	v_fmac_f32_e32 v221, v222, v194
	s_andn2_b64 vcc, exec, s[8:9]
	s_cbranch_vccz .Lg1_470
.Lg1_465:
	s_cmpk_lt_u32 s68, 0x102
	s_cbranch_scc0 .LBB0_438
	s_mov_b32 s68, s5
	s_branch .Lg1_457

; __global__ void __launch_bounds__(NTHR) fwd_kernel(Args args) {
;     ...
;     for (int l = 0; l < 2; ++l) {
;         for (int b = 0; b < NB; ++b) {
;             const int nTileIn = b == 0 ? NT_ALL : NT_LAT, nTile = (l == 0 && b == 0) ? NT_ALL : NT_LAT, nRows = nTile * 256;
.Lmy_tramp165:
	s_branch .LBB0_165
